# static priority raise for waves 0-3 during the attention phase (on top of the GEMM-phase raise for waves 0-3)
# speedup vs baseline: 1.0025x; 1.0025x over previous
; __device__ __forceinline__ const float* kin(kptr_t p, int i) { return (const float*)(const GAS float*)*(const unsigned long long __attribute__((address_space(4)))*)(p + 8 * i); }
; #define TID() int lane_v_; asm volatile("v_mbcnt_lo_u32_b32 %0, -1, 0\n\tv_mbcnt_hi_u32_b32 %0, -1, %0" : "=v"(lane_v_)); const int tid = wave_s * 64 + lane_v_
; #define PTRS() kptr_t kp = kargs(); unsigned char* ws = kws(kp); (void)ws
; __global__ void __launch_bounds__(NTHR, 2) hybrid_fwd(Args a) {
;     ...
;     if (IN(2)) for (int rep_ = 0; rep_ < REPS(2); ++rep_) { TID(); PTRS(); attn_phase(lds, QKVZ, kin(kp, I_ASINK), S1, G, bid, tid); }
.LBB0_224:
	v_readlane_b32 s2, v254, 1
	v_readlane_b32 s3, v254, 2
	s_cmp_lt_i32 s2, 3
	s_cselect_b64 s[2:3], -1, 0
	s_and_b64 s[2:3], s[2:3], s[0:1]
	s_andn2_b64 vcc, exec, s[2:3]
	s_cbranch_vccnz .LBB0_248
	v_readlane_b32 s98, v254, 3
	s_cmp_ge_u32 s98, 0x100
	s_cbranch_scc1 .Lmy_prio_2
	s_setprio 1
